# removed conservative vmcnt(0) before the thread-id asm fence at static item starts (gdn1, prep, lru, gdnfin)
# baseline (speedup 1.0000x reference)
.LBB0_98:
	v_mov_b32_e32 v20, v133
	s_waitcnt lgkmcnt(0)
	s_barrier
	s_load_dwordx2 s[6:7], s[0:1], 0x130
	v_ashrrev_i32_e32 v10, 2, v20
	v_ashrrev_i32_e32 v11, 31, v10
	v_lshlrev_b64 v[12:13], 7, v[10:11]
	v_and_b32_e32 v0, 3, v20
	v_lshl_or_b32 v2, v0, 5, v12
	v_mov_b32_e32 v3, v13
	s_waitcnt lgkmcnt(0)
	v_lshl_add_u64 v[2:3], s[6:7], 0, v[2:3]
	v_lshl_add_u64 v[6:7], v[2:3], 0, s[8:9]
	global_load_dwordx4 v[2:5], v[6:7], off
	s_nop 0
	global_load_dwordx4 v[6:9], v[6:7], off offset:-16
	v_lshlrev_b32_e32 v0, 5, v20
	v_mul_lo_u32 v14, v10, s17
	v_and_b32_e32 v0, 0x60, v0
	v_add3_u32 v10, 0, v14, v0
	s_mov_b64 s[10:11], 0xec27800
	s_ashr_i32 s5, s4, 31
	s_movk_i32 s3, 0x7f
	v_and_b32_e32 v18, 63, v20
	v_cmp_lt_i32_e32 vcc, s3, v20
	v_lshl_add_u64 v[150:151], s[6:7], 0, v[12:13]
	v_lshl_add_u64 v[150:151], v[150:151], 0, v[0:1]
	v_lshl_add_u64 v[152:153], v[150:151], 0, s[10:11]
	s_lshl_b64 s[10:11], s[4:5], 13
	v_lshl_add_u64 v[154:155], v[152:153], 0, s[10:11]
	global_load_dwordx4 v[134:137], v[154:155], off offset:16
	global_load_dwordx4 v[138:141], v[154:155], off
	s_add_i32 s10, s4, 1
	s_ashr_i32 s11, s10, 31
	s_lshl_b64 s[12:13], s[10:11], 13
	v_lshl_add_u64 v[154:155], v[152:153], 0, s[12:13]
	global_load_dwordx4 v[142:145], v[154:155], off offset:16
	global_load_dwordx4 v[146:149], v[154:155], off
	v_ashrrev_i32_e32 v19, 6, v20
	s_mov_b64 s[12:13], exec
	s_andn2_b64 exec, exec, vcc
	v_add_u32_e32 v156, s4, v19
	v_lshlrev_b32_e32 v156, 10, v156
	v_lshl_add_u32 v156, v18, 2, v156
	v_add_u32_e32 v156, 0x327800, v156
	v_mov_b32_e32 v157, 0
	v_lshl_add_u64 v[156:157], s[6:7], 0, v[156:157]
	global_load_dword v160, v[156:157], off
	s_mov_b64 exec, s[12:13]
	s_waitcnt vmcnt(0)
	ds_write_b128 v10, v[6:9]
	ds_write_b128 v10, v[2:5] offset:16
	v_add3_u32 v0, 0, v0, v14
	ds_write_b128 v0, v[138:141] offset:9216
	ds_write_b128 v0, v[134:137] offset:9232
	ds_write_b128 v0, v[146:149] offset:18432
	ds_write_b128 v0, v[142:145] offset:18448
	s_and_saveexec_b64 s[12:13], vcc
	s_xor_b64 s[12:13], exec, s[12:13]
	s_or_saveexec_b64 s[12:13], s[12:13]
	s_xor_b64 exec, exec, s[12:13]
	s_cbranch_execz .LBB0_97
	v_lshl_add_u32 v4, v20, 2, 0
	ds_write_b32 v4, v160 offset:44288
	s_branch .LBB0_97

.LBB0_396:
	s_cmpk_gt_u32 s16, 0x5ff
	s_cbranch_scc0 .LBB0_493
	s_cmpk_gt_u32 s16, 0x63f
	s_cbranch_scc0 .LBB0_475
	v_mov_b32_e32 v29, v133
	s_load_dwordx2 s[4:5], s[0:1], 0x130
	s_lshl_b32 s3, s16, 3
	v_ashrrev_i32_e32 v0, 5, v29
	s_addk_i32 s3, 0xce00
	v_and_b32_e32 v0, -2, v0
	v_and_b32_e32 v12, 63, v29
	v_add_u32_e32 v13, s3, v0
	s_waitcnt lgkmcnt(0)
	v_mov_b64_e32 v[2:3], s[4:5]
	v_mad_i64_i32 v[2:3], s[6:7], v13, s33, v[2:3]
	v_lshlrev_b32_e32 v0, 1, v12
	v_lshl_add_u64 v[2:3], v[2:3], 0, v[0:1]
	v_add_co_u32_e32 v14, vcc, 0x4b27000, v2
	s_mov_b64 s[6:7], 0x4b27800
	s_nop 0
	v_addc_co_u32_e32 v15, vcc, 0, v3, vcc
	v_add_co_u32_e32 v16, vcc, 0x4b28000, v2
	s_mov_b32 s3, 0x4b29000
	s_nop 0
	v_addc_co_u32_e32 v17, vcc, 0, v3, vcc
	v_lshl_add_u64 v[10:11], v[2:3], 0, s[6:7]
	s_mov_b64 s[6:7], 0x4b28c40
	v_add_co_u32_e32 v46, vcc, s3, v2
	v_lshl_add_u64 v[6:7], v[2:3], 0, s[6:7]
	global_load_ushort v42, v[16:17], off offset:2176
	global_load_ushort v40, v[16:17], off offset:2304
	global_load_ushort v39, v[16:17], off offset:2432
	global_load_ushort v38, v[16:17], off offset:2560
	global_load_ushort v36, v[16:17], off offset:2688
	global_load_ushort v31, v[16:17], off offset:2816
	global_load_ushort v32, v[16:17], off offset:2944
	global_load_ushort v30, v[16:17], off offset:3136
	global_load_ushort v41, v[10:11], off offset:128
	global_load_ushort v8, v[10:11], off offset:256
	global_load_ushort v5, v[10:11], off offset:384
	global_load_ushort v4, v[10:11], off offset:512
	global_load_ushort v44, v[10:11], off offset:640
	global_load_ushort v33, v[10:11], off offset:768
	global_load_ushort v34, v[10:11], off offset:896
	global_load_ushort v28, v[6:7], off offset:128
	v_addc_co_u32_e32 v47, vcc, 0, v3, vcc
	global_load_ushort v45, v[14:15], off offset:2048
	global_load_ushort v43, v[16:17], off offset:2048
	global_load_ushort v27, v[6:7], off offset:256
	global_load_ushort v26, v[6:7], off offset:384
	global_load_ushort v25, v[6:7], off offset:512
	global_load_ushort v24, v[6:7], off offset:640
	global_load_ushort v14, v[6:7], off offset:768
	global_load_ushort v15, v[6:7], off offset:896
	global_load_ushort v23, v[46:47], off offset:3136
	global_load_ushort v22, v[46:47], off offset:3264
	global_load_ushort v21, v[46:47], off offset:3392
	global_load_ushort v20, v[46:47], off offset:3520
	global_load_ushort v19, v[46:47], off offset:3648
	global_load_ushort v18, v[46:47], off offset:3776
	global_load_ushort v16, v[46:47], off offset:3904
	global_load_ushort v17, v[46:47], off offset:4032
	v_cmp_gt_i32_e64 s[8:9], s40, v13
	v_cmp_lt_i32_e64 s[10:11], s41, v13
	v_mov_b32_e32 v35, 1.0
	v_mov_b32_e32 v37, 0
	s_and_saveexec_b64 s[6:7], s[10:11]
	s_cbranch_execz .LBB0_400
	v_and_b32_e32 v9, 15, v29
	v_cvt_f32_ubyte0_e32 v9, v9
	v_mul_f32_e32 v9, 0xbf135d8e, v9
	v_mul_f32_e32 v9, 0x3fb8aa3b, v9
	v_lshrrev_b32_e32 v0, 6, v13
	v_exp_f32_e32 v9, v9
	v_cmp_gt_u32_e32 vcc, 32, v12
	s_nop 1
	v_cndmask_b32_e32 v0, v13, v0, vcc
	v_and_b32_e32 v0, 63, v0
	v_cvt_f32_ubyte0_e32 v0, v0
	v_mul_f32_e32 v0, v9, v0
	v_mul_f32_e32 v0, 0.15915494, v0
	v_cos_f32_e32 v35, v0
	v_sin_f32_e32 v37, v0

.LBB0_494:
	s_add_i32 s3, s16, 0xfffffc00
	s_lshl_b32 s10, s3, 5
	s_cmpk_gt_u32 s3, 0xff
	s_movk_i32 s4, 0x100
	s_cselect_b32 s8, 0x1000, s4
	s_movk_i32 s4, 0x1f00
	s_cselect_b32 s4, 0x3000, s4
	s_and_b32 s4, s4, s10
	s_add_i32 s11, s10, -2
	v_mov_b32_e32 v18, v133
	s_sub_i32 s9, s11, s4
	s_load_dwordx2 s[6:7], s[0:1], 0x130
	s_waitcnt lgkmcnt(0)
	s_barrier
	s_load_dwordx4 s[20:23], s[0:1], 0x90
	s_cmp_gt_i32 s9, -1
	s_cselect_b64 s[4:5], -1, 0
	s_cmp_lt_u32 s9, s8
	s_cselect_b64 s[18:19], -1, 0
	s_and_b64 s[18:19], s[4:5], s[18:19]
	s_waitcnt lgkmcnt(0)
	s_add_u32 s20, s20, s14
	s_addc_u32 s21, s21, s15
	v_ashrrev_i32_e32 v19, 31, v18
	v_lshl_add_u64 v[8:9], v[18:19], 2, s[20:21]
	global_load_dword v2, v[8:9], off
	global_load_dword v4, v[8:9], off offset:1024
	global_load_dword v3, v[8:9], off offset:2048
	global_load_dword v0, v[8:9], off offset:3072
	v_add_u32_e32 v8, s47, v18
	v_mov_b32_e32 v6, s22
	v_mov_b32_e32 v7, s23
	v_ashrrev_i32_e32 v9, 31, v8
	v_lshl_add_u64 v[6:7], v[8:9], 2, v[6:7]
	global_load_dword v5, v[6:7], off
	v_mov_b32_e32 v6, 0
	s_andn2_b64 vcc, exec, s[18:19]
	v_mov_b32_e32 v7, 0
	s_cbranch_vccnz .LBB0_496
	s_mul_hi_u32 s17, s11, 0x1440
	s_mulk_i32 s11, 0x1440
	s_add_u32 s18, s6, s11
	s_addc_u32 s19, s7, s17
	v_lshl_add_u64 v[8:9], v[18:19], 1, s[18:19]
	v_add_co_u32_e32 v8, vcc, 0x4b27000, v8
	s_nop 1
	v_addc_co_u32_e32 v9, vcc, 0, v9, vcc
	global_load_ushort v7, v[8:9], off offset:3072

.LBB0_569:
	s_lshl_b32 s4, s16, 4
	s_and_b32 s3, s16, 3
	s_and_b32 s53, s4, 0xffffffc0
	s_cmpk_gt_i32 s53, 0x1fff
	s_movk_i32 s5, 0x100
	s_cselect_b32 s17, 0x1000, s5
	s_movk_i32 s5, 0xff00
	s_cselect_b32 s5, 0xfffff000, s5
	v_mov_b32_e32 v47, v133
	s_and_b32 s43, s5, s4
	s_load_dwordx2 s[4:5], s[0:1], 0x130
	s_load_dwordx2 s[6:7], s[0:1], 0xc8
	s_add_i32 s18, s53, -2
	s_sub_i32 s10, s18, s43
	v_and_b32_e32 v46, 63, v47
	s_waitcnt lgkmcnt(0)
	s_add_u32 s8, s4, 0x4b27800
	s_addc_u32 s9, s5, 0
	s_mul_i32 s11, s62, 0x3000
	s_add_u32 s6, s6, s11
	s_mul_hi_i32 s11, s62, 0x3000
	v_lshl_or_b32 v50, s3, 6, v46
	s_addc_u32 s7, s7, s11
	v_lshlrev_b32_e32 v0, 2, v50
	v_lshl_add_u64 v[2:3], s[6:7], 0, v[0:1]
	v_add_co_u32_e32 v4, vcc, s69, v2
	v_ashrrev_i32_e32 v49, 6, v47
	s_nop 0
	v_addc_co_u32_e32 v5, vcc, 0, v3, vcc
	v_add_co_u32_e32 v10, vcc, 0x2000, v2
	v_lshlrev_b32_e32 v48, 4, v49
	s_nop 0
	v_addc_co_u32_e32 v11, vcc, 0, v3, vcc
	global_load_dword v6, v0, s[6:7]
	global_load_dword v7, v0, s[6:7] offset:3072
	global_load_dword v8, v[4:5], off offset:2048
	global_load_dword v9, v[10:11], off offset:1024
	v_add_u32_e32 v4, s10, v48
	v_lshlrev_b32_e32 v0, 1, v50
	v_cmp_lt_i32_e32 vcc, -1, v4
	v_cmp_gt_i32_e64 s[6:7], s17, v4
	v_lshl_add_u64 v[44:45], s[8:9], 0, v[0:1]
	s_and_b64 s[10:11], vcc, s[6:7]
	v_mov_b32_e32 v43, 0
	v_add_u32_e32 v51, s18, v48
	v_mov_b32_e32 v42, 0
	s_and_saveexec_b64 s[6:7], s[10:11]
	s_cbranch_execz .LBB0_571
	v_mad_i64_i32 v[10:11], s[18:19], v51, s33, v[44:45]
	global_load_ushort v42, v[10:11], off offset:2048
